# v53 + attention softmax range check: the 16-deep dependent v_max3 chain split into two independent chains
# speedup vs baseline: 1.0033x; 1.0033x over previous
; __device__ __forceinline__ void partialSM(f32x16& p0, f32x16& p1, float& m_reg, float& mn, float& alpha) {
;   constexpr float C = SCALE * 1.4426950408889634f;
;   float pmax = p0[0]; for (int r = 1; r < 16; ++r) pmax = fmaxf(pmax, p0[r]); for (int r = 0; r < 16; ++r) pmax = fmaxf(pmax, p1[r]);
;   { auto rr = __builtin_amdgcn_permlane32_swap(__float_as_uint(pmax), __float_as_uint(pmax), false, false);
;     pmax = fmaxf(__uint_as_float(rr[0]), __uint_as_float(rr[1])); }
;   if (__builtin_expect(__all(pmax - m_reg <= THR / SCALE), 1)) { mn = m_reg; alpha = 1.f; }
;   else { mn = fmaxf(m_reg, pmax); alpha = __builtin_amdgcn_exp2f((m_reg - mn) * C); m_reg = mn; }
;   float mnC = -mn * C;
;   for (int r = 0; r < 16; ++r) p0[r] = fmaf(p0[r], C, mnC); for (int r = 0; r < 16; ++r) p1[r] = fmaf(p1[r], C, mnC);
;   for (int r = 0; r < 16; ++r) p0[r] = __builtin_amdgcn_exp2f(p0[r]);
; }
; __device__ __forceinline__ void finishSM(f32x16& p0, f32x16& p1, float alpha, float& l_reg, bf16x8& pa0, bf16x8& pa1, bf16x8& pa2, bf16x8& pa3) {
;   for (int r = 0; r < 16; ++r) p1[r] = __builtin_amdgcn_exp2f(p1[r]);
;   float ps = 0; for (int r = 0; r < 16; ++r) ps += p0[r]; for (int r = 0; r < 16; ++r) ps += p1[r];
;   { auto rr = __builtin_amdgcn_permlane32_swap(__float_as_uint(ps), __float_as_uint(ps), false, false);
;     ps = __uint_as_float(rr[0]) + __uint_as_float(rr[1]); }
;   l_reg = l_reg * alpha + ps;
;     ...
;   PK4(p0, 0, pa0); PK4(p0, 8, pa1); PK4(p1, 0, pa2); PK4(p1, 8, pa3);
;     ...
; }
; __device__ __forceinline__ void qkt(f32x16& p0, f32x16& p1, const char* Kn, const char* Kp, const bf16x8* qr, int r32, int hi) {
;   p0 = f32x16{}; p1 = f32x16{};
; #pragma unroll
;   for (int d0 = 0; d0 < 8; ++d0) { int cb = (d0 * 16 + hi * 8) * 2;
;     bf16x8 b0 = *reinterpret_cast<const bf16x8*>(Kn + KSWZ(r32, cb));
;     bf16x8 b1 = *reinterpret_cast<const bf16x8*>(Kn + KSWZ(32 + r32, cb));
;     p0 = __builtin_amdgcn_mfma_f32_32x32x16_bf16(b0, qr[d0], p0, 0, 0, 0);
;     p1 = __builtin_amdgcn_mfma_f32_32x32x16_bf16(b1, qr[d0], p1, 0, 0, 0); }
; #pragma unroll
;   for (int d1 = 0; d1 < 4; ++d1) { int cb = (d1 * 16 + hi * 8) * 2;
;     bf16x8 b0 = *reinterpret_cast<const bf16x8*>(Kp + KPSWZ(r32, cb));
;     bf16x8 b1 = *reinterpret_cast<const bf16x8*>(Kp + KPSWZ(32 + r32, cb));
;     p0 = __builtin_amdgcn_mfma_f32_32x32x16_bf16(b0, qr[8 + d1], p0, 0, 0, 0);
.Lpp_loop:
	s_barrier
	ds_read_b128 v[192:195], v160 offset:16384
	ds_read_b128 v[196:199], v160 offset:24576
	ds_read_b128 v[200:203], v161 offset:16384
	ds_read_b128 v[204:207], v161 offset:24576
	ds_read_b128 v[208:211], v162 offset:16384
	ds_read_b128 v[212:215], v162 offset:24576
	ds_read_b128 v[216:219], v163 offset:16384
	ds_read_b128 v[220:223], v163 offset:24576
	v_max3_f32 v250, v80, v81, v82
	v_max3_f32 v251, v83, v84, v85
	v_max3_f32 v250, v250, v86, v87
	v_max3_f32 v251, v251, v88, v89
	v_max3_f32 v250, v250, v90, v91
	v_max3_f32 v251, v251, v92, v93
	v_max3_f32 v250, v250, v94, v95
	v_max3_f32 v251, v251, v64, v65
	v_max3_f32 v250, v250, v66, v67
	v_max3_f32 v251, v251, v68, v69
	v_max3_f32 v250, v250, v70, v71
	v_max3_f32 v251, v251, v72, v73
	v_max3_f32 v250, v250, v74, v75
	v_max3_f32 v251, v251, v76, v77
	v_max3_f32 v250, v250, v78, v79
	v_max_f32_e32 v250, v250, v251
	v_cmp_lt_f32_e64 vcc, s64, |v250|
	s_waitcnt vmcnt(0)
	ds_write_b128 v246, v[232:235]
	ds_write_b128 v246, v[236:239] offset:8192
	ds_write_b128 v248, v[240:243]
	ds_write_b128 v244, v[224:227]
	ds_write_b128 v244, v[228:231] offset:8192
	global_load_dwordx4 v[232:235], v180, s[50:51]
	global_load_dwordx4 v[236:239], v180, s[52:53]
	global_load_dwordx4 v[224:227], v180, s[54:55] offset:256
	global_load_dwordx4 v[228:231], v180, s[56:57] offset:256
	global_load_dwordx4 v[240:243], v181, s[58:59]
	s_cmp_lg_u32 s62, 0
	s_cbranch_scc1 .Lpp_safe_Ba
	s_cbranch_vccnz .Lpp_sw_Ba
	v_exp_f32_e32 v80, v80
	v_exp_f32_e32 v81, v81
	v_exp_f32_e32 v82, v82
	v_exp_f32_e32 v83, v83
	v_exp_f32_e32 v84, v84
	v_exp_f32_e32 v85, v85
	v_exp_f32_e32 v86, v86
	v_exp_f32_e32 v87, v87
	v_exp_f32_e32 v88, v88
	v_exp_f32_e32 v89, v89
	v_exp_f32_e32 v90, v90
	v_exp_f32_e32 v91, v91
	v_exp_f32_e32 v92, v92
	v_exp_f32_e32 v93, v93
	v_exp_f32_e32 v94, v94
	v_exp_f32_e32 v95, v95
	v_exp_f32_e32 v64, v64
	v_exp_f32_e32 v65, v65
	v_exp_f32_e32 v66, v66
	v_exp_f32_e32 v67, v67
	v_exp_f32_e32 v68, v68
	v_exp_f32_e32 v69, v69
	v_exp_f32_e32 v70, v70
	v_exp_f32_e32 v71, v71
	v_exp_f32_e32 v72, v72
	v_exp_f32_e32 v73, v73
	v_exp_f32_e32 v74, v74
	v_exp_f32_e32 v75, v75
	v_exp_f32_e32 v76, v76
	v_exp_f32_e32 v77, v77
	v_exp_f32_e32 v78, v78
	v_exp_f32_e32 v79, v79
	v_add_f32_e32 v249, v80, v81
	v_add_f32_e32 v250, v82, v83
	v_add_f32_e32 v251, v84, v85
	v_add_f32_e32 v182, v86, v87
	v_add_f32_e32 v249, v88, v249
	v_add_f32_e32 v250, v89, v250
	v_add_f32_e32 v251, v90, v251
	v_add_f32_e32 v182, v91, v182
	v_add_f32_e32 v249, v92, v249
	v_add_f32_e32 v250, v93, v250
	v_add_f32_e32 v251, v94, v251
	v_add_f32_e32 v182, v95, v182
	v_add_f32_e32 v249, v64, v249
	v_add_f32_e32 v250, v65, v250
	v_add_f32_e32 v251, v66, v251
	v_add_f32_e32 v182, v67, v182
	v_add_f32_e32 v249, v68, v249
	v_add_f32_e32 v250, v69, v250
	v_add_f32_e32 v251, v70, v251
	v_add_f32_e32 v182, v71, v182
	v_add_f32_e32 v249, v72, v249
	v_add_f32_e32 v250, v73, v250
	v_add_f32_e32 v251, v74, v251
	v_add_f32_e32 v182, v75, v182
	v_add_f32_e32 v249, v76, v249
	v_add_f32_e32 v250, v77, v250
	v_add_f32_e32 v251, v78, v251
	v_add_f32_e32 v182, v79, v182
	v_add_f32_e32 v249, v249, v250
	v_add_f32_e32 v251, v251, v182
	v_add_f32_e32 v249, v249, v251
	v_add_f32_e32 v176, v176, v249
	v_cvt_pk_bf16_f32 v144, v80, v81
	v_cvt_pk_bf16_f32 v145, v82, v83
	v_cvt_pk_bf16_f32 v146, v84, v85
	v_cvt_pk_bf16_f32 v147, v86, v87
	v_cvt_pk_bf16_f32 v148, v88, v89
	v_cvt_pk_bf16_f32 v149, v90, v91
	v_cvt_pk_bf16_f32 v150, v92, v93
	v_cvt_pk_bf16_f32 v151, v94, v95
	v_cvt_pk_bf16_f32 v152, v64, v65
	v_cvt_pk_bf16_f32 v153, v66, v67
	v_cvt_pk_bf16_f32 v154, v68, v69
	v_cvt_pk_bf16_f32 v155, v70, v71
	v_cvt_pk_bf16_f32 v156, v72, v73
	v_cvt_pk_bf16_f32 v157, v74, v75
	v_cvt_pk_bf16_f32 v158, v76, v77
	v_cvt_pk_bf16_f32 v159, v78, v79
.Lpp_send_Ba:
	s_add_i32 s11, s11, 1
	s_waitcnt lgkmcnt(6)
	v_mfma_f32_32x32x16_bf16 v[80:95], v[192:195], v[136:139], 0
	v_mfma_f32_32x32x16_bf16 v[64:79], v[196:199], v[136:139], 0
	s_add_i32 s36, s35, 2
	s_min_u32 s36, s36, 67
	s_lshl_b32 s44, s36, 6
	ds_read_b128 v[192:195], v164 offset:16384
	ds_read_b128 v[196:199], v164 offset:24576
	s_waitcnt lgkmcnt(6)
	v_mfma_f32_32x32x16_bf16 v[80:95], v[200:203], v[132:135], v[80:95]
	v_mfma_f32_32x32x16_bf16 v[64:79], v[204:207], v[132:135], v[64:79]
	s_add_i32 s45, s31, s44
	s_add_i32 s46, s24, s44
	s_add_i32 s46, s46, 0xffffff00
	ds_read_b128 v[200:203], v165 offset:16384
	ds_read_b128 v[204:207], v165 offset:24576
	s_waitcnt lgkmcnt(6)
	v_mfma_f32_32x32x16_bf16 v[80:95], v[208:211], v[128:131], v[80:95]
	v_mfma_f32_32x32x16_bf16 v[64:79], v[212:215], v[128:131], v[64:79]
	s_cmp_lt_u32 s36, 4
	s_cselect_b32 s36, s45, s46
	s_add_i32 s37, s35, 1
	ds_read_b128 v[208:211], v166 offset:16384
	ds_read_b128 v[212:215], v166 offset:24576
	s_waitcnt lgkmcnt(6)
	v_mfma_f32_32x32x16_bf16 v[80:95], v[216:219], v[124:127], v[80:95]
	v_mfma_f32_32x32x16_bf16 v[64:79], v[220:223], v[124:127], v[64:79]
	s_min_u32 s37, s37, 67
	s_lshl_b32 s44, s37, 6
	s_add_i32 s45, s31, s44
	ds_read_b128 v[216:219], v167 offset:16384
	ds_read_b128 v[220:223], v167 offset:24576
	s_waitcnt lgkmcnt(6)
	v_mfma_f32_32x32x16_bf16 v[80:95], v[192:195], v[120:123], v[80:95]
	v_mfma_f32_32x32x16_bf16 v[64:79], v[196:199], v[120:123], v[64:79]
	s_add_i32 s46, s24, s44
	s_add_i32 s46, s46, 0xffffff00
	s_cmp_lt_u32 s37, 4
	ds_read_b128 v[192:195], v168 offset:8192
	ds_read_b128 v[196:199], v168 offset:12288
	s_waitcnt lgkmcnt(6)
	v_mfma_f32_32x32x16_bf16 v[80:95], v[200:203], v[140:143], v[80:95]
	v_mfma_f32_32x32x16_bf16 v[64:79], v[204:207], v[140:143], v[64:79]
	s_cselect_b32 s37, s45, s46
	s_add_i32 s35, s35, 1
	s_lshl_b32 s44, s36, 12
	ds_read_b128 v[200:203], v169 offset:8192
	ds_read_b128 v[204:207], v169 offset:12288
	s_waitcnt lgkmcnt(6)
; __device__ __forceinline__ void qkt(f32x16& p0, f32x16& p1, const char* Kn, const char* Kp, const bf16x8* qr, int r32, int hi) {
;   p0 = f32x16{}; p1 = f32x16{};
; #pragma unroll
;   for (int d0 = 0; d0 < 8; ++d0) { int cb = (d0 * 16 + hi * 8) * 2;
;     bf16x8 b0 = *reinterpret_cast<const bf16x8*>(Kn + KSWZ(r32, cb));
;     bf16x8 b1 = *reinterpret_cast<const bf16x8*>(Kn + KSWZ(32 + r32, cb));
;     p0 = __builtin_amdgcn_mfma_f32_32x32x16_bf16(b0, qr[d0], p0, 0, 0, 0);
;     p1 = __builtin_amdgcn_mfma_f32_32x32x16_bf16(b1, qr[d0], p1, 0, 0, 0); }
; #pragma unroll
;   for (int d1 = 0; d1 < 4; ++d1) { int cb = (d1 * 16 + hi * 8) * 2;
;     bf16x8 b0 = *reinterpret_cast<const bf16x8*>(Kp + KPSWZ(r32, cb));
;     bf16x8 b1 = *reinterpret_cast<const bf16x8*>(Kp + KPSWZ(32 + r32, cb));
;     p0 = __builtin_amdgcn_mfma_f32_32x32x16_bf16(b0, qr[8 + d1], p0, 0, 0, 0);
;     p1 = __builtin_amdgcn_mfma_f32_32x32x16_bf16(b1, qr[8 + d1], p1, 0, 0, 0); }
; }
; __device__ __forceinline__ int v_st(int k, int c) { const int kk = (k & ~0xC) | ((k & 4) << 1) | ((k & 8) >> 1); return ((kk >> 3) * 4 + (c >> 5)) * 512 + ((kk & 7) * 32 + (c & 31)) * 2; }
; __device__ __forceinline__ int v_rd_base(int lane) { return ((lane & 3) << 3) | (((lane >> 2) & 3) << 6) | (((lane >> 4) & 1) << 5) | (((lane >> 5) & 1) << 8); }
; template <int OFF> __device__ __forceinline__ s16x4 tr_read(int vb) {
;   s16x4 r; asm volatile("ds_read_b64_tr_b16 %0, %1 offset:%2" : "=&v"(r) : "v"(vb), "i"(OFF) : "memory"); return r;
; }
; template <int D0> __device__ __forceinline__ void pv_one(f32x16& od, int vb, bf16x8 pa0, bf16x8 pa1, bf16x8 pa2, bf16x8 pa3) {
;   const s16x4 l0 = tr_read<v_rd_off(D0, 0, 0)>(vb), h0 = tr_read<v_rd_off(D0, 0, 1)>(vb), l1 = tr_read<v_rd_off(D0, 1, 0)>(vb), h1 = tr_read<v_rd_off(D0, 1, 1)>(vb);
;   const s16x4 l2 = tr_read<v_rd_off(D0, 2, 0)>(vb), h2 = tr_read<v_rd_off(D0, 2, 1)>(vb), l3 = tr_read<v_rd_off(D0, 3, 0)>(vb), h3 = tr_read<v_rd_off(D0, 3, 1)>(vb);
;   asm volatile("s_waitcnt lgkmcnt(0)" ::: "memory"); SBAR();
;     ...
;   od = __builtin_amdgcn_mfma_f32_32x32x16_bf16(pa0, PK(l0, h0), od, 0, 0, 0);
;   od = __builtin_amdgcn_mfma_f32_32x32x16_bf16(pa1, PK(l1, h1), od, 0, 0, 0);
;   od = __builtin_amdgcn_mfma_f32_32x32x16_bf16(pa2, PK(l2, h2), od, 0, 0, 0);
;   od = __builtin_amdgcn_mfma_f32_32x32x16_bf16(pa3, PK(l3, h3), od, 0, 0, 0);
;     ...
; }
	v_mfma_f32_32x32x16_bf16 v[80:95], v[208:211], v[116:119], v[80:95]
	v_mfma_f32_32x32x16_bf16 v[64:79], v[212:215], v[116:119], v[64:79]
	s_add_u32 s50, s47, s44
	s_addc_u32 s51, s63, 0
	s_add_u32 s52, s50, 0x20000
	ds_read_b128 v[208:211], v170 offset:8192
	ds_read_b128 v[212:215], v170 offset:12288
	s_waitcnt lgkmcnt(6)
	v_mfma_f32_32x32x16_bf16 v[80:95], v[216:219], v[112:115], v[80:95]
	v_mfma_f32_32x32x16_bf16 v[64:79], v[220:223], v[112:115], v[64:79]
	s_addc_u32 s53, s51, 0
	s_lshl_b32 s44, s37, 12
	s_add_u32 s54, s47, s44
	ds_read_b128 v[216:219], v171 offset:8192
	ds_read_b128 v[220:223], v171 offset:12288
	s_waitcnt lgkmcnt(6)
	v_mfma_f32_32x32x16_bf16 v[80:95], v[192:195], v[108:111], v[80:95]
	v_mfma_f32_32x32x16_bf16 v[64:79], v[196:199], v[108:111], v[64:79]
	s_addc_u32 s55, s63, 0
	s_add_u32 s56, s54, 0x20000
	s_addc_u32 s57, s55, 0
	ds_read_b64_tr_b16 v[192:193], v174 offset:0
	ds_read_b64_tr_b16 v[194:195], v174 offset:2048
	ds_read_b64_tr_b16 v[196:197], v174 offset:4096
	ds_read_b64_tr_b16 v[198:199], v174 offset:6144
	s_waitcnt lgkmcnt(8)
	v_mfma_f32_32x32x16_bf16 v[80:95], v[200:203], v[104:107], v[80:95]
	v_mfma_f32_32x32x16_bf16 v[64:79], v[204:207], v[104:107], v[64:79]
	s_lshl_b32 s44, s36, 10
	s_add_u32 s58, s60, s44
	s_addc_u32 s59, s61, 0
	ds_read_b64_tr_b16 v[200:201], v174 offset:8192
	ds_read_b64_tr_b16 v[202:203], v174 offset:10240
	ds_read_b64_tr_b16 v[204:205], v174 offset:12288
	ds_read_b64_tr_b16 v[206:207], v174 offset:14336
	s_waitcnt lgkmcnt(10)
	v_mfma_f32_32x32x16_bf16 v[80:95], v[208:211], v[100:103], v[80:95]
	v_mfma_f32_32x32x16_bf16 v[64:79], v[212:215], v[100:103], v[64:79]
	ds_read_b64_tr_b16 v[208:209], v174 offset:512
	ds_read_b64_tr_b16 v[210:211], v174 offset:2560
	ds_read_b64_tr_b16 v[212:213], v174 offset:4608
	ds_read_b64_tr_b16 v[214:215], v174 offset:6656
	s_waitcnt lgkmcnt(12)
	v_mfma_f32_32x32x16_bf16 v[80:95], v[216:219], v[96:99], v[80:95]
	v_mfma_f32_32x32x16_bf16 v[64:79], v[220:223], v[96:99], v[64:79]
	ds_read_b64_tr_b16 v[216:217], v174 offset:8704
	ds_read_b64_tr_b16 v[218:219], v174 offset:10752
	ds_read_b64_tr_b16 v[220:221], v174 offset:12800
	ds_read_b64_tr_b16 v[222:223], v174 offset:14848
	s_waitcnt lgkmcnt(12)
	v_mfma_f32_32x32x16_bf16 v[0:15], v[144:147], v[192:195], v[0:15]
	ds_read_b64_tr_b16 v[192:193], v174 offset:1024
	ds_read_b64_tr_b16 v[194:195], v174 offset:3072
	v_mfma_f32_32x32x16_bf16 v[0:15], v[148:151], v[196:199], v[0:15]
	ds_read_b64_tr_b16 v[196:197], v174 offset:5120
	ds_read_b64_tr_b16 v[198:199], v174 offset:7168
	s_waitcnt lgkmcnt(12)
	v_mfma_f32_32x32x16_bf16 v[0:15], v[152:155], v[200:203], v[0:15]
	ds_read_b64_tr_b16 v[200:201], v174 offset:9216
	ds_read_b64_tr_b16 v[202:203], v174 offset:11264
	v_mfma_f32_32x32x16_bf16 v[0:15], v[156:159], v[204:207], v[0:15]
	ds_read_b64_tr_b16 v[204:205], v174 offset:13312
	ds_read_b64_tr_b16 v[206:207], v174 offset:15360
	s_waitcnt lgkmcnt(12)
	v_mfma_f32_32x32x16_bf16 v[48:63], v[144:147], v[208:211], v[48:63]
	ds_read_b64_tr_b16 v[208:209], v174 offset:1536
	ds_read_b64_tr_b16 v[210:211], v174 offset:3584
	v_mfma_f32_32x32x16_bf16 v[48:63], v[148:151], v[212:215], v[48:63]
	ds_read_b64_tr_b16 v[212:213], v174 offset:5632
	ds_read_b64_tr_b16 v[214:215], v174 offset:7680
	s_waitcnt lgkmcnt(12)
	v_mfma_f32_32x32x16_bf16 v[48:63], v[152:155], v[216:219], v[48:63]
	ds_read_b64_tr_b16 v[216:217], v174 offset:9728
	ds_read_b64_tr_b16 v[218:219], v174 offset:11776
	v_mfma_f32_32x32x16_bf16 v[48:63], v[156:159], v[220:223], v[48:63]
	ds_read_b64_tr_b16 v[220:221], v174 offset:13824
	ds_read_b64_tr_b16 v[222:223], v174 offset:15872
	s_waitcnt lgkmcnt(12)
	v_mfma_f32_32x32x16_bf16 v[32:47], v[144:147], v[192:195], v[32:47]
	v_mfma_f32_32x32x16_bf16 v[32:47], v[148:151], v[196:199], v[32:47]
	s_waitcnt lgkmcnt(8)
	v_mfma_f32_32x32x16_bf16 v[32:47], v[152:155], v[200:203], v[32:47]
	v_mfma_f32_32x32x16_bf16 v[32:47], v[156:159], v[204:207], v[32:47]
	s_waitcnt lgkmcnt(4)
	v_mfma_f32_32x32x16_bf16 v[16:31], v[144:147], v[208:211], v[16:31]
	v_mfma_f32_32x32x16_bf16 v[16:31], v[148:151], v[212:215], v[16:31]
	s_waitcnt lgkmcnt(0)
	v_mfma_f32_32x32x16_bf16 v[16:31], v[152:155], v[216:219], v[16:31]
	v_mfma_f32_32x32x16_bf16 v[16:31], v[156:159], v[220:223], v[16:31]
	s_barrier
; __device__ __forceinline__ void partialSM(f32x16& p0, f32x16& p1, float& m_reg, float& mn, float& alpha) {
;   constexpr float C = SCALE * 1.4426950408889634f;
;   float pmax = p0[0]; for (int r = 1; r < 16; ++r) pmax = fmaxf(pmax, p0[r]); for (int r = 0; r < 16; ++r) pmax = fmaxf(pmax, p1[r]);
;   { auto rr = __builtin_amdgcn_permlane32_swap(__float_as_uint(pmax), __float_as_uint(pmax), false, false);
;     pmax = fmaxf(__uint_as_float(rr[0]), __uint_as_float(rr[1])); }
;   if (__builtin_expect(__all(pmax - m_reg <= THR / SCALE), 1)) { mn = m_reg; alpha = 1.f; }
;   else { mn = fmaxf(m_reg, pmax); alpha = __builtin_amdgcn_exp2f((m_reg - mn) * C); m_reg = mn; }
;   float mnC = -mn * C;
;   for (int r = 0; r < 16; ++r) p0[r] = fmaf(p0[r], C, mnC); for (int r = 0; r < 16; ++r) p1[r] = fmaf(p1[r], C, mnC);
;   for (int r = 0; r < 16; ++r) p0[r] = __builtin_amdgcn_exp2f(p0[r]);
; }
; __device__ __forceinline__ void finishSM(f32x16& p0, f32x16& p1, float alpha, float& l_reg, bf16x8& pa0, bf16x8& pa1, bf16x8& pa2, bf16x8& pa3) {
;   for (int r = 0; r < 16; ++r) p1[r] = __builtin_amdgcn_exp2f(p1[r]);
;   float ps = 0; for (int r = 0; r < 16; ++r) ps += p0[r]; for (int r = 0; r < 16; ++r) ps += p1[r];
;   { auto rr = __builtin_amdgcn_permlane32_swap(__float_as_uint(ps), __float_as_uint(ps), false, false);
;     ps = __uint_as_float(rr[0]) + __uint_as_float(rr[1]); }
;   l_reg = l_reg * alpha + ps;
;     ...
;   PK4(p0, 0, pa0); PK4(p0, 8, pa1); PK4(p1, 0, pa2); PK4(p1, 8, pa3);
;     ...
; }
	ds_read_b128 v[192:195], v160
	ds_read_b128 v[196:199], v160 offset:8192
	ds_read_b128 v[200:203], v161
	ds_read_b128 v[204:207], v161 offset:8192
	ds_read_b128 v[208:211], v162
	ds_read_b128 v[212:215], v162 offset:8192
	ds_read_b128 v[216:219], v163
	ds_read_b128 v[220:223], v163 offset:8192
	v_max3_f32 v250, v80, v81, v82
	v_max3_f32 v251, v83, v84, v85
	v_max3_f32 v250, v250, v86, v87
	v_max3_f32 v251, v251, v88, v89
	v_max3_f32 v250, v250, v90, v91
	v_max3_f32 v251, v251, v92, v93
	v_max3_f32 v250, v250, v94, v95
	v_max3_f32 v251, v251, v64, v65
	v_max3_f32 v250, v250, v66, v67
	v_max3_f32 v251, v251, v68, v69
	v_max3_f32 v250, v250, v70, v71
	v_max3_f32 v251, v251, v72, v73
	v_max3_f32 v250, v250, v74, v75
	v_max3_f32 v251, v251, v76, v77
	v_max3_f32 v250, v250, v78, v79
	v_max_f32_e32 v250, v250, v251
	v_cmp_lt_f32_e64 vcc, s64, |v250|
	s_waitcnt vmcnt(0)
	ds_write_b128 v247, v[232:235]
	ds_write_b128 v247, v[236:239] offset:8192
	ds_write_b128 v183, v[240:243]
	ds_write_b128 v245, v[224:227]
	ds_write_b128 v245, v[228:231] offset:8192
	global_load_dwordx4 v[232:235], v180, s[50:51]
	global_load_dwordx4 v[236:239], v180, s[52:53]
	global_load_dwordx4 v[224:227], v180, s[54:55] offset:256
	global_load_dwordx4 v[228:231], v180, s[56:57] offset:256
	global_load_dwordx4 v[240:243], v181, s[58:59]
	s_cmp_lg_u32 s62, 0
	s_cbranch_scc1 .Lpp_safe_Bb
	s_cbranch_vccnz .Lpp_sw_Bb
	v_exp_f32_e32 v80, v80
	v_exp_f32_e32 v81, v81
	v_exp_f32_e32 v82, v82
	v_exp_f32_e32 v83, v83
	v_exp_f32_e32 v84, v84
	v_exp_f32_e32 v85, v85
	v_exp_f32_e32 v86, v86
	v_exp_f32_e32 v87, v87
	v_exp_f32_e32 v88, v88
	v_exp_f32_e32 v89, v89
	v_exp_f32_e32 v90, v90
	v_exp_f32_e32 v91, v91
	v_exp_f32_e32 v92, v92
	v_exp_f32_e32 v93, v93
	v_exp_f32_e32 v94, v94
	v_exp_f32_e32 v95, v95
	v_exp_f32_e32 v64, v64
	v_exp_f32_e32 v65, v65
	v_exp_f32_e32 v66, v66
	v_exp_f32_e32 v67, v67
	v_exp_f32_e32 v68, v68
	v_exp_f32_e32 v69, v69
	v_exp_f32_e32 v70, v70
	v_exp_f32_e32 v71, v71
	v_exp_f32_e32 v72, v72
	v_exp_f32_e32 v73, v73
	v_exp_f32_e32 v74, v74
	v_exp_f32_e32 v75, v75
	v_exp_f32_e32 v76, v76
	v_exp_f32_e32 v77, v77
	v_exp_f32_e32 v78, v78
	v_exp_f32_e32 v79, v79
	v_add_f32_e32 v249, v80, v81
	v_add_f32_e32 v250, v82, v83
	v_add_f32_e32 v251, v84, v85
	v_add_f32_e32 v182, v86, v87
	v_add_f32_e32 v249, v88, v249
	v_add_f32_e32 v250, v89, v250
	v_add_f32_e32 v251, v90, v251
	v_add_f32_e32 v182, v91, v182
	v_add_f32_e32 v249, v92, v249
	v_add_f32_e32 v250, v93, v250
	v_add_f32_e32 v251, v94, v251
	v_add_f32_e32 v182, v95, v182
	v_add_f32_e32 v249, v64, v249
	v_add_f32_e32 v250, v65, v250
	v_add_f32_e32 v251, v66, v251
	v_add_f32_e32 v182, v67, v182
	v_add_f32_e32 v249, v68, v249
	v_add_f32_e32 v250, v69, v250
	v_add_f32_e32 v251, v70, v251
	v_add_f32_e32 v182, v71, v182
	v_add_f32_e32 v249, v72, v249
	v_add_f32_e32 v250, v73, v250
	v_add_f32_e32 v251, v74, v251
	v_add_f32_e32 v182, v75, v182
	v_add_f32_e32 v249, v76, v249
	v_add_f32_e32 v250, v77, v250
	v_add_f32_e32 v251, v78, v251
	v_add_f32_e32 v182, v79, v182
	v_add_f32_e32 v249, v249, v250
	v_add_f32_e32 v251, v251, v182
	v_add_f32_e32 v249, v249, v251
	v_add_f32_e32 v176, v176, v249
	v_cvt_pk_bf16_f32 v144, v80, v81
	v_cvt_pk_bf16_f32 v145, v82, v83
	v_cvt_pk_bf16_f32 v146, v84, v85
	v_cvt_pk_bf16_f32 v147, v86, v87
	v_cvt_pk_bf16_f32 v148, v88, v89
	v_cvt_pk_bf16_f32 v149, v90, v91
	v_cvt_pk_bf16_f32 v150, v92, v93
	v_cvt_pk_bf16_f32 v151, v94, v95
	v_cvt_pk_bf16_f32 v152, v64, v65
	v_cvt_pk_bf16_f32 v153, v66, v67
	v_cvt_pk_bf16_f32 v154, v68, v69
	v_cvt_pk_bf16_f32 v155, v70, v71
	v_cvt_pk_bf16_f32 v156, v72, v73
	v_cvt_pk_bf16_f32 v157, v74, v75
	v_cvt_pk_bf16_f32 v158, v76, v77
	v_cvt_pk_bf16_f32 v159, v78, v79

; __device__ __forceinline__ void partialSM(f32x16& p0, f32x16& p1, float& m_reg, float& mn, float& alpha) {
;   constexpr float C = SCALE * 1.4426950408889634f;
;   float pmax = p0[0]; for (int r = 1; r < 16; ++r) pmax = fmaxf(pmax, p0[r]); for (int r = 0; r < 16; ++r) pmax = fmaxf(pmax, p1[r]);
;   { auto rr = __builtin_amdgcn_permlane32_swap(__float_as_uint(pmax), __float_as_uint(pmax), false, false);
;     pmax = fmaxf(__uint_as_float(rr[0]), __uint_as_float(rr[1])); }
;   if (__builtin_expect(__all(pmax - m_reg <= THR / SCALE), 1)) { mn = m_reg; alpha = 1.f; }
;   else { mn = fmaxf(m_reg, pmax); alpha = __builtin_amdgcn_exp2f((m_reg - mn) * C); m_reg = mn; }
;   float mnC = -mn * C;
;   for (int r = 0; r < 16; ++r) p0[r] = fmaf(p0[r], C, mnC); for (int r = 0; r < 16; ++r) p1[r] = fmaf(p1[r], C, mnC);
;   for (int r = 0; r < 16; ++r) p0[r] = __builtin_amdgcn_exp2f(p0[r]);
; }
; __device__ __forceinline__ void finishSM(f32x16& p0, f32x16& p1, float alpha, float& l_reg, bf16x8& pa0, bf16x8& pa1, bf16x8& pa2, bf16x8& pa3) {
;   for (int r = 0; r < 16; ++r) p1[r] = __builtin_amdgcn_exp2f(p1[r]);
;   float ps = 0; for (int r = 0; r < 16; ++r) ps += p0[r]; for (int r = 0; r < 16; ++r) ps += p1[r];
;   { auto rr = __builtin_amdgcn_permlane32_swap(__float_as_uint(ps), __float_as_uint(ps), false, false);
;     ps = __uint_as_float(rr[0]) + __uint_as_float(rr[1]); }
;   l_reg = l_reg * alpha + ps;
;     ...
;   PK4(p0, 0, pa0); PK4(p0, 8, pa1); PK4(p1, 0, pa2); PK4(p1, 8, pa3);
;     ...
; }
; __device__ __forceinline__ void qkt(f32x16& p0, f32x16& p1, const char* Kn, const char* Kp, const bf16x8* qr, int r32, int hi) {
;   p0 = f32x16{}; p1 = f32x16{};
; #pragma unroll
;   for (int d0 = 0; d0 < 8; ++d0) { int cb = (d0 * 16 + hi * 8) * 2;
;     bf16x8 b0 = *reinterpret_cast<const bf16x8*>(Kn + KSWZ(r32, cb));
;     bf16x8 b1 = *reinterpret_cast<const bf16x8*>(Kn + KSWZ(32 + r32, cb));
;     p0 = __builtin_amdgcn_mfma_f32_32x32x16_bf16(b0, qr[d0], p0, 0, 0, 0);
;     p1 = __builtin_amdgcn_mfma_f32_32x32x16_bf16(b1, qr[d0], p1, 0, 0, 0); }
; #pragma unroll
;   for (int d1 = 0; d1 < 4; ++d1) { int cb = (d1 * 16 + hi * 8) * 2;
;     bf16x8 b0 = *reinterpret_cast<const bf16x8*>(Kp + KPSWZ(r32, cb));
;     bf16x8 b1 = *reinterpret_cast<const bf16x8*>(Kp + KPSWZ(32 + r32, cb));
;     p0 = __builtin_amdgcn_mfma_f32_32x32x16_bf16(b0, qr[8 + d1], p0, 0, 0, 0);
.Lpp_aloop:
	v_max3_f32 v250, v80, v81, v82
	v_max3_f32 v251, v83, v84, v85
	v_max3_f32 v250, v250, v86, v87
	v_max3_f32 v251, v251, v88, v89
	v_max3_f32 v250, v250, v90, v91
	v_max3_f32 v251, v251, v92, v93
	v_max3_f32 v250, v250, v94, v95
	v_max3_f32 v251, v251, v64, v65
	v_max3_f32 v250, v250, v66, v67
	v_max3_f32 v251, v251, v68, v69
	v_max3_f32 v250, v250, v70, v71
	v_max3_f32 v251, v251, v72, v73
	v_max3_f32 v250, v250, v74, v75
	v_max3_f32 v251, v251, v76, v77
	v_max3_f32 v250, v250, v78, v79
	v_max_f32_e32 v250, v250, v251
	v_cmp_lt_f32_e64 vcc, s64, |v250|
	s_waitcnt vmcnt(0)
	ds_write_b128 v246, v[232:235]
	ds_write_b128 v246, v[236:239] offset:8192
	ds_write_b128 v248, v[240:243]
	ds_write_b128 v244, v[224:227]
	ds_write_b128 v244, v[228:231] offset:8192
	global_load_dwordx4 v[232:235], v180, s[50:51]
	global_load_dwordx4 v[236:239], v180, s[52:53]
	global_load_dwordx4 v[224:227], v180, s[54:55] offset:256
	global_load_dwordx4 v[228:231], v180, s[56:57] offset:256
	global_load_dwordx4 v[240:243], v181, s[58:59]
	s_cmp_lg_u32 s62, 0
	s_cbranch_scc1 .Lpp_safe_Aa
	s_cbranch_vccnz .Lpp_sw_Aa
	v_exp_f32_e32 v80, v80
	v_exp_f32_e32 v81, v81
	v_exp_f32_e32 v82, v82
	v_exp_f32_e32 v83, v83
	v_exp_f32_e32 v84, v84
	v_exp_f32_e32 v85, v85
	v_exp_f32_e32 v86, v86
	v_exp_f32_e32 v87, v87
	v_exp_f32_e32 v88, v88
	v_exp_f32_e32 v89, v89
	v_exp_f32_e32 v90, v90
	v_exp_f32_e32 v91, v91
	v_exp_f32_e32 v92, v92
	v_exp_f32_e32 v93, v93
	v_exp_f32_e32 v94, v94
	v_exp_f32_e32 v95, v95
	v_exp_f32_e32 v64, v64
	v_exp_f32_e32 v65, v65
	v_exp_f32_e32 v66, v66
	v_exp_f32_e32 v67, v67
	v_exp_f32_e32 v68, v68
	v_exp_f32_e32 v69, v69
	v_exp_f32_e32 v70, v70
	v_exp_f32_e32 v71, v71
	v_exp_f32_e32 v72, v72
	v_exp_f32_e32 v73, v73
	v_exp_f32_e32 v74, v74
	v_exp_f32_e32 v75, v75
	v_exp_f32_e32 v76, v76
	v_exp_f32_e32 v77, v77
	v_exp_f32_e32 v78, v78
	v_exp_f32_e32 v79, v79
	v_add_f32_e32 v249, v80, v81
	v_add_f32_e32 v250, v82, v83
	v_add_f32_e32 v251, v84, v85
	v_add_f32_e32 v182, v86, v87
	v_add_f32_e32 v249, v88, v249
	v_add_f32_e32 v250, v89, v250
	v_add_f32_e32 v251, v90, v251
	v_add_f32_e32 v182, v91, v182
	v_add_f32_e32 v249, v92, v249
	v_add_f32_e32 v250, v93, v250
	v_add_f32_e32 v251, v94, v251
	v_add_f32_e32 v182, v95, v182
	v_add_f32_e32 v249, v64, v249
	v_add_f32_e32 v250, v65, v250
	v_add_f32_e32 v251, v66, v251
	v_add_f32_e32 v182, v67, v182
	v_add_f32_e32 v249, v68, v249
	v_add_f32_e32 v250, v69, v250
	v_add_f32_e32 v251, v70, v251
	v_add_f32_e32 v182, v71, v182
	v_add_f32_e32 v249, v72, v249
	v_add_f32_e32 v250, v73, v250
	v_add_f32_e32 v251, v74, v251
	v_add_f32_e32 v182, v75, v182
	v_add_f32_e32 v249, v76, v249
	v_add_f32_e32 v250, v77, v250
	v_add_f32_e32 v251, v78, v251
	v_add_f32_e32 v182, v79, v182
	v_add_f32_e32 v249, v249, v250
	v_add_f32_e32 v251, v251, v182
	v_add_f32_e32 v249, v249, v251
	v_add_f32_e32 v176, v176, v249
	v_cvt_pk_bf16_f32 v144, v80, v81
	v_cvt_pk_bf16_f32 v145, v82, v83
	v_cvt_pk_bf16_f32 v146, v84, v85
	v_cvt_pk_bf16_f32 v147, v86, v87
	v_cvt_pk_bf16_f32 v148, v88, v89
	v_cvt_pk_bf16_f32 v149, v90, v91
	v_cvt_pk_bf16_f32 v150, v92, v93
	v_cvt_pk_bf16_f32 v151, v94, v95
	v_cvt_pk_bf16_f32 v152, v64, v65
	v_cvt_pk_bf16_f32 v153, v66, v67
	v_cvt_pk_bf16_f32 v154, v68, v69
	v_cvt_pk_bf16_f32 v155, v70, v71
	v_cvt_pk_bf16_f32 v156, v72, v73
	v_cvt_pk_bf16_f32 v157, v74, v75
	v_cvt_pk_bf16_f32 v158, v76, v77
	v_cvt_pk_bf16_f32 v159, v78, v79
.Lpp_send_Aa:
	s_waitcnt lgkmcnt(0)
	s_barrier
	s_add_i32 s11, s11, 1
	ds_read_b128 v[192:195], v160 offset:16384
	ds_read_b128 v[196:199], v160 offset:24576
	ds_read_b128 v[200:203], v161 offset:16384
	ds_read_b128 v[204:207], v161 offset:24576
	ds_read_b128 v[208:211], v162 offset:16384
	ds_read_b128 v[212:215], v162 offset:24576
	ds_read_b128 v[216:219], v163 offset:16384
	ds_read_b128 v[220:223], v163 offset:24576
	s_waitcnt lgkmcnt(6)
	v_mfma_f32_32x32x16_bf16 v[80:95], v[192:195], v[136:139], 0
	v_mfma_f32_32x32x16_bf16 v[64:79], v[196:199], v[136:139], 0
	s_add_i32 s36, s35, 2
	s_min_u32 s36, s36, 67
	s_lshl_b32 s44, s36, 6
	ds_read_b128 v[192:195], v164 offset:16384
	ds_read_b128 v[196:199], v164 offset:24576
	s_waitcnt lgkmcnt(6)
	v_mfma_f32_32x32x16_bf16 v[80:95], v[200:203], v[132:135], v[80:95]
	v_mfma_f32_32x32x16_bf16 v[64:79], v[204:207], v[132:135], v[64:79]
	s_add_i32 s45, s31, s44
	s_add_i32 s46, s24, s44
	s_add_i32 s46, s46, 0xffffff00
	ds_read_b128 v[200:203], v165 offset:16384
	ds_read_b128 v[204:207], v165 offset:24576
	s_waitcnt lgkmcnt(6)
	v_mfma_f32_32x32x16_bf16 v[80:95], v[208:211], v[128:131], v[80:95]
	v_mfma_f32_32x32x16_bf16 v[64:79], v[212:215], v[128:131], v[64:79]
	s_cmp_lt_u32 s36, 4
	s_cselect_b32 s36, s45, s46
	s_add_i32 s37, s35, 1
	ds_read_b128 v[208:211], v166 offset:16384
	ds_read_b128 v[212:215], v166 offset:24576
	s_waitcnt lgkmcnt(6)
	v_mfma_f32_32x32x16_bf16 v[80:95], v[216:219], v[124:127], v[80:95]
	v_mfma_f32_32x32x16_bf16 v[64:79], v[220:223], v[124:127], v[64:79]
	s_min_u32 s37, s37, 67
	s_lshl_b32 s44, s37, 6
	s_add_i32 s45, s31, s44
	ds_read_b128 v[216:219], v167 offset:16384
	ds_read_b128 v[220:223], v167 offset:24576
	s_waitcnt lgkmcnt(6)
	v_mfma_f32_32x32x16_bf16 v[80:95], v[192:195], v[120:123], v[80:95]
	v_mfma_f32_32x32x16_bf16 v[64:79], v[196:199], v[120:123], v[64:79]
	s_add_i32 s46, s24, s44
	s_add_i32 s46, s46, 0xffffff00
	s_cmp_lt_u32 s37, 4
	ds_read_b128 v[192:195], v168 offset:8192
	ds_read_b128 v[196:199], v168 offset:12288
	s_waitcnt lgkmcnt(6)
	v_mfma_f32_32x32x16_bf16 v[80:95], v[200:203], v[140:143], v[80:95]
	v_mfma_f32_32x32x16_bf16 v[64:79], v[204:207], v[140:143], v[64:79]
	s_cselect_b32 s37, s45, s46
	s_add_i32 s35, s35, 1
	s_lshl_b32 s44, s36, 12
	ds_read_b128 v[200:203], v169 offset:8192
	ds_read_b128 v[204:207], v169 offset:12288
	s_waitcnt lgkmcnt(6)
; __device__ __forceinline__ void qkt(f32x16& p0, f32x16& p1, const char* Kn, const char* Kp, const bf16x8* qr, int r32, int hi) {
;   p0 = f32x16{}; p1 = f32x16{};
; #pragma unroll
;   for (int d0 = 0; d0 < 8; ++d0) { int cb = (d0 * 16 + hi * 8) * 2;
;     bf16x8 b0 = *reinterpret_cast<const bf16x8*>(Kn + KSWZ(r32, cb));
;     bf16x8 b1 = *reinterpret_cast<const bf16x8*>(Kn + KSWZ(32 + r32, cb));
;     p0 = __builtin_amdgcn_mfma_f32_32x32x16_bf16(b0, qr[d0], p0, 0, 0, 0);
;     p1 = __builtin_amdgcn_mfma_f32_32x32x16_bf16(b1, qr[d0], p1, 0, 0, 0); }
; #pragma unroll
;   for (int d1 = 0; d1 < 4; ++d1) { int cb = (d1 * 16 + hi * 8) * 2;
;     bf16x8 b0 = *reinterpret_cast<const bf16x8*>(Kp + KPSWZ(r32, cb));
;     bf16x8 b1 = *reinterpret_cast<const bf16x8*>(Kp + KPSWZ(32 + r32, cb));
;     p0 = __builtin_amdgcn_mfma_f32_32x32x16_bf16(b0, qr[8 + d1], p0, 0, 0, 0);
;     p1 = __builtin_amdgcn_mfma_f32_32x32x16_bf16(b1, qr[8 + d1], p1, 0, 0, 0); }
; }
; __device__ __forceinline__ int v_st(int k, int c) { const int kk = (k & ~0xC) | ((k & 4) << 1) | ((k & 8) >> 1); return ((kk >> 3) * 4 + (c >> 5)) * 512 + ((kk & 7) * 32 + (c & 31)) * 2; }
; __device__ __forceinline__ int v_rd_base(int lane) { return ((lane & 3) << 3) | (((lane >> 2) & 3) << 6) | (((lane >> 4) & 1) << 5) | (((lane >> 5) & 1) << 8); }
; template <int OFF> __device__ __forceinline__ s16x4 tr_read(int vb) {
;   s16x4 r; asm volatile("ds_read_b64_tr_b16 %0, %1 offset:%2" : "=&v"(r) : "v"(vb), "i"(OFF) : "memory"); return r;
; }
; template <int D0> __device__ __forceinline__ void pv_one(f32x16& od, int vb, bf16x8 pa0, bf16x8 pa1, bf16x8 pa2, bf16x8 pa3) {
;   const s16x4 l0 = tr_read<v_rd_off(D0, 0, 0)>(vb), h0 = tr_read<v_rd_off(D0, 0, 1)>(vb), l1 = tr_read<v_rd_off(D0, 1, 0)>(vb), h1 = tr_read<v_rd_off(D0, 1, 1)>(vb);
;   const s16x4 l2 = tr_read<v_rd_off(D0, 2, 0)>(vb), h2 = tr_read<v_rd_off(D0, 2, 1)>(vb), l3 = tr_read<v_rd_off(D0, 3, 0)>(vb), h3 = tr_read<v_rd_off(D0, 3, 1)>(vb);
;   asm volatile("s_waitcnt lgkmcnt(0)" ::: "memory"); SBAR();
;     ...
;   od = __builtin_amdgcn_mfma_f32_32x32x16_bf16(pa0, PK(l0, h0), od, 0, 0, 0);
;   od = __builtin_amdgcn_mfma_f32_32x32x16_bf16(pa1, PK(l1, h1), od, 0, 0, 0);
;   od = __builtin_amdgcn_mfma_f32_32x32x16_bf16(pa2, PK(l2, h2), od, 0, 0, 0);
;   od = __builtin_amdgcn_mfma_f32_32x32x16_bf16(pa3, PK(l3, h3), od, 0, 0, 0);
;     ...
; }
	v_mfma_f32_32x32x16_bf16 v[80:95], v[208:211], v[116:119], v[80:95]
	v_mfma_f32_32x32x16_bf16 v[64:79], v[212:215], v[116:119], v[64:79]
	s_add_u32 s50, s47, s44
	s_addc_u32 s51, s63, 0
	s_add_u32 s52, s50, 0x20000
	ds_read_b128 v[208:211], v170 offset:8192
	ds_read_b128 v[212:215], v170 offset:12288
	s_waitcnt lgkmcnt(6)
	v_mfma_f32_32x32x16_bf16 v[80:95], v[216:219], v[112:115], v[80:95]
	v_mfma_f32_32x32x16_bf16 v[64:79], v[220:223], v[112:115], v[64:79]
	s_addc_u32 s53, s51, 0
	s_lshl_b32 s44, s37, 12
	s_add_u32 s54, s47, s44
	ds_read_b128 v[216:219], v171 offset:8192
	ds_read_b128 v[220:223], v171 offset:12288
	s_waitcnt lgkmcnt(6)
	v_mfma_f32_32x32x16_bf16 v[80:95], v[192:195], v[108:111], v[80:95]
	v_mfma_f32_32x32x16_bf16 v[64:79], v[196:199], v[108:111], v[64:79]
	s_addc_u32 s55, s63, 0
	s_add_u32 s56, s54, 0x20000
	s_addc_u32 s57, s55, 0
	ds_read_b64_tr_b16 v[192:193], v174 offset:0
	ds_read_b64_tr_b16 v[194:195], v174 offset:2048
	ds_read_b64_tr_b16 v[196:197], v174 offset:4096
	ds_read_b64_tr_b16 v[198:199], v174 offset:6144
	s_waitcnt lgkmcnt(8)
	v_mfma_f32_32x32x16_bf16 v[80:95], v[200:203], v[104:107], v[80:95]
	v_mfma_f32_32x32x16_bf16 v[64:79], v[204:207], v[104:107], v[64:79]
	s_lshl_b32 s44, s36, 10
	s_add_u32 s58, s60, s44
	s_addc_u32 s59, s61, 0
	ds_read_b64_tr_b16 v[200:201], v174 offset:8192
	ds_read_b64_tr_b16 v[202:203], v174 offset:10240
	ds_read_b64_tr_b16 v[204:205], v174 offset:12288
	ds_read_b64_tr_b16 v[206:207], v174 offset:14336
	s_waitcnt lgkmcnt(10)
	v_mfma_f32_32x32x16_bf16 v[80:95], v[208:211], v[100:103], v[80:95]
	v_mfma_f32_32x32x16_bf16 v[64:79], v[212:215], v[100:103], v[64:79]
	ds_read_b64_tr_b16 v[208:209], v174 offset:512
	ds_read_b64_tr_b16 v[210:211], v174 offset:2560
	ds_read_b64_tr_b16 v[212:213], v174 offset:4608
	ds_read_b64_tr_b16 v[214:215], v174 offset:6656
	s_waitcnt lgkmcnt(12)
	v_mfma_f32_32x32x16_bf16 v[80:95], v[216:219], v[96:99], v[80:95]
	v_mfma_f32_32x32x16_bf16 v[64:79], v[220:223], v[96:99], v[64:79]
	ds_read_b64_tr_b16 v[216:217], v174 offset:8704
	ds_read_b64_tr_b16 v[218:219], v174 offset:10752
	ds_read_b64_tr_b16 v[220:221], v174 offset:12800
	ds_read_b64_tr_b16 v[222:223], v174 offset:14848
	s_waitcnt lgkmcnt(12)
	v_mfma_f32_32x32x16_bf16 v[0:15], v[144:147], v[192:195], v[0:15]
	ds_read_b64_tr_b16 v[192:193], v174 offset:1024
	ds_read_b64_tr_b16 v[194:195], v174 offset:3072
	v_mfma_f32_32x32x16_bf16 v[0:15], v[148:151], v[196:199], v[0:15]
	ds_read_b64_tr_b16 v[196:197], v174 offset:5120
	ds_read_b64_tr_b16 v[198:199], v174 offset:7168
	s_waitcnt lgkmcnt(12)
	v_mfma_f32_32x32x16_bf16 v[0:15], v[152:155], v[200:203], v[0:15]
	ds_read_b64_tr_b16 v[200:201], v174 offset:9216
	ds_read_b64_tr_b16 v[202:203], v174 offset:11264
	v_mfma_f32_32x32x16_bf16 v[0:15], v[156:159], v[204:207], v[0:15]
	ds_read_b64_tr_b16 v[204:205], v174 offset:13312
	ds_read_b64_tr_b16 v[206:207], v174 offset:15360
	s_waitcnt lgkmcnt(12)
	v_mfma_f32_32x32x16_bf16 v[48:63], v[144:147], v[208:211], v[48:63]
	ds_read_b64_tr_b16 v[208:209], v174 offset:1536
	ds_read_b64_tr_b16 v[210:211], v174 offset:3584
	v_mfma_f32_32x32x16_bf16 v[48:63], v[148:151], v[212:215], v[48:63]
	ds_read_b64_tr_b16 v[212:213], v174 offset:5632
	ds_read_b64_tr_b16 v[214:215], v174 offset:7680
	s_waitcnt lgkmcnt(12)
	v_mfma_f32_32x32x16_bf16 v[48:63], v[152:155], v[216:219], v[48:63]
	ds_read_b64_tr_b16 v[216:217], v174 offset:9728
	ds_read_b64_tr_b16 v[218:219], v174 offset:11776
	v_mfma_f32_32x32x16_bf16 v[48:63], v[156:159], v[220:223], v[48:63]
	ds_read_b64_tr_b16 v[220:221], v174 offset:13824
	ds_read_b64_tr_b16 v[222:223], v174 offset:15872
	s_waitcnt lgkmcnt(12)
	v_mfma_f32_32x32x16_bf16 v[32:47], v[144:147], v[192:195], v[32:47]
	v_mfma_f32_32x32x16_bf16 v[32:47], v[148:151], v[196:199], v[32:47]
	s_waitcnt lgkmcnt(8)
	v_mfma_f32_32x32x16_bf16 v[32:47], v[152:155], v[200:203], v[32:47]
	v_mfma_f32_32x32x16_bf16 v[32:47], v[156:159], v[204:207], v[32:47]
	s_waitcnt lgkmcnt(4)
	v_mfma_f32_32x32x16_bf16 v[16:31], v[144:147], v[208:211], v[16:31]
	v_mfma_f32_32x32x16_bf16 v[16:31], v[148:151], v[212:215], v[16:31]
	s_waitcnt lgkmcnt(0)
	v_mfma_f32_32x32x16_bf16 v[16:31], v[152:155], v[216:219], v[16:31]
	v_mfma_f32_32x32x16_bf16 v[16:31], v[156:159], v[220:223], v[16:31]
	v_max3_f32 v250, v80, v81, v82
	v_max3_f32 v251, v83, v84, v85
	v_max3_f32 v250, v250, v86, v87
	v_max3_f32 v251, v251, v88, v89
	v_max3_f32 v250, v250, v90, v91
	v_max3_f32 v251, v251, v92, v93
	v_max3_f32 v250, v250, v94, v95
	v_max3_f32 v251, v251, v64, v65
	v_max3_f32 v250, v250, v66, v67
	v_max3_f32 v251, v251, v68, v69
	v_max3_f32 v250, v250, v70, v71
	v_max3_f32 v251, v251, v72, v73
	v_max3_f32 v250, v250, v74, v75
	v_max3_f32 v251, v251, v76, v77
	v_max3_f32 v250, v250, v78, v79
	v_max_f32_e32 v250, v250, v251
	v_cmp_lt_f32_e64 vcc, s64, |v250|
	s_waitcnt vmcnt(0)
	ds_write_b128 v247, v[232:235]
	ds_write_b128 v247, v[236:239] offset:8192
	ds_write_b128 v183, v[240:243]
	ds_write_b128 v245, v[224:227]
	ds_write_b128 v245, v[228:231] offset:8192
	global_load_dwordx4 v[232:235], v180, s[50:51]
	global_load_dwordx4 v[236:239], v180, s[52:53]
	global_load_dwordx4 v[224:227], v180, s[54:55] offset:256
	global_load_dwordx4 v[228:231], v180, s[56:57] offset:256
	global_load_dwordx4 v[240:243], v181, s[58:59]
	s_cmp_lg_u32 s62, 0
	s_cbranch_scc1 .Lpp_safe_Ab
; __device__ __forceinline__ void finishSM(f32x16& p0, f32x16& p1, float alpha, float& l_reg, bf16x8& pa0, bf16x8& pa1, bf16x8& pa2, bf16x8& pa3) {
;   for (int r = 0; r < 16; ++r) p1[r] = __builtin_amdgcn_exp2f(p1[r]);
;   float ps = 0; for (int r = 0; r < 16; ++r) ps += p0[r]; for (int r = 0; r < 16; ++r) ps += p1[r];
;   { auto rr = __builtin_amdgcn_permlane32_swap(__float_as_uint(ps), __float_as_uint(ps), false, false);
;     ps = __uint_as_float(rr[0]) + __uint_as_float(rr[1]); }
;   l_reg = l_reg * alpha + ps;
;     ...
;   PK4(p0, 0, pa0); PK4(p0, 8, pa1); PK4(p1, 0, pa2); PK4(p1, 8, pa3);
;     ...
; }
	s_cbranch_vccnz .Lpp_sw_Ab
	v_exp_f32_e32 v80, v80
	v_exp_f32_e32 v81, v81
	v_exp_f32_e32 v82, v82
	v_exp_f32_e32 v83, v83
	v_exp_f32_e32 v84, v84
	v_exp_f32_e32 v85, v85
	v_exp_f32_e32 v86, v86
	v_exp_f32_e32 v87, v87
	v_exp_f32_e32 v88, v88
	v_exp_f32_e32 v89, v89
	v_exp_f32_e32 v90, v90
	v_exp_f32_e32 v91, v91
	v_exp_f32_e32 v92, v92
	v_exp_f32_e32 v93, v93
	v_exp_f32_e32 v94, v94
	v_exp_f32_e32 v95, v95
	v_exp_f32_e32 v64, v64
	v_exp_f32_e32 v65, v65
	v_exp_f32_e32 v66, v66
	v_exp_f32_e32 v67, v67
	v_exp_f32_e32 v68, v68
	v_exp_f32_e32 v69, v69
	v_exp_f32_e32 v70, v70
	v_exp_f32_e32 v71, v71
	v_exp_f32_e32 v72, v72
	v_exp_f32_e32 v73, v73
	v_exp_f32_e32 v74, v74
	v_exp_f32_e32 v75, v75
	v_exp_f32_e32 v76, v76
	v_exp_f32_e32 v77, v77
	v_exp_f32_e32 v78, v78
	v_exp_f32_e32 v79, v79
	v_add_f32_e32 v249, v80, v81
	v_add_f32_e32 v250, v82, v83
	v_add_f32_e32 v251, v84, v85
	v_add_f32_e32 v182, v86, v87
	v_add_f32_e32 v249, v88, v249
	v_add_f32_e32 v250, v89, v250
	v_add_f32_e32 v251, v90, v251
	v_add_f32_e32 v182, v91, v182
	v_add_f32_e32 v249, v92, v249
	v_add_f32_e32 v250, v93, v250
	v_add_f32_e32 v251, v94, v251
	v_add_f32_e32 v182, v95, v182
	v_add_f32_e32 v249, v64, v249
	v_add_f32_e32 v250, v65, v250
	v_add_f32_e32 v251, v66, v251
	v_add_f32_e32 v182, v67, v182
	v_add_f32_e32 v249, v68, v249
	v_add_f32_e32 v250, v69, v250
	v_add_f32_e32 v251, v70, v251
	v_add_f32_e32 v182, v71, v182
	v_add_f32_e32 v249, v72, v249
	v_add_f32_e32 v250, v73, v250
	v_add_f32_e32 v251, v74, v251
	v_add_f32_e32 v182, v75, v182
	v_add_f32_e32 v249, v76, v249
	v_add_f32_e32 v250, v77, v250
	v_add_f32_e32 v251, v78, v251
	v_add_f32_e32 v182, v79, v182
	v_add_f32_e32 v249, v249, v250
	v_add_f32_e32 v251, v251, v182
	v_add_f32_e32 v249, v249, v251
	v_add_f32_e32 v176, v176, v249
	v_cvt_pk_bf16_f32 v144, v80, v81
	v_cvt_pk_bf16_f32 v145, v82, v83
	v_cvt_pk_bf16_f32 v146, v84, v85
	v_cvt_pk_bf16_f32 v147, v86, v87
	v_cvt_pk_bf16_f32 v148, v88, v89
	v_cvt_pk_bf16_f32 v149, v90, v91
	v_cvt_pk_bf16_f32 v150, v92, v93
	v_cvt_pk_bf16_f32 v151, v94, v95
	v_cvt_pk_bf16_f32 v152, v64, v65
	v_cvt_pk_bf16_f32 v153, v66, v67
	v_cvt_pk_bf16_f32 v154, v68, v69
	v_cvt_pk_bf16_f32 v155, v70, v71
	v_cvt_pk_bf16_f32 v156, v72, v73
	v_cvt_pk_bf16_f32 v157, v74, v75
	v_cvt_pk_bf16_f32 v158, v76, v77
	v_cvt_pk_bf16_f32 v159, v78, v79
